# adds LN1 and combine LayerNorm-parameter staging loops: second pair of loads issued before the first wait
# speedup vs baseline: 1.0069x; 1.0069x over previous
; #define LAS __attribute__((address_space(3)))
; __device__ __forceinline__ void stage_ln_params(const float* g, const float* b, LAS float* gL, LAS float* bL, int tid) {
;     for (int i = tid; i < D_; i += 512) { gL[i] = g[i]; bL[i] = b[i]; }
; }
.LBB0_576:
	v_ashrrev_i32_e32 v9, 31, v2
	v_mov_b32_e32 v8, v2
	v_ashrrev_i32_e32 v7, 31, v3
	v_mov_b32_e32 v6, v3
	v_lshlrev_b64 v[8:9], 2, v[8:9]
	v_lshl_add_u64 v[10:11], s[12:13], 0, v[8:9]
	v_lshlrev_b64 v[6:7], 2, v[6:7]
	v_lshl_add_u64 v[12:13], s[12:13], 0, v[6:7]
	global_load_dword v10, v[10:11], off
	s_nop 0
	global_load_dword v11, v[12:13], off
	v_add_u32_e32 v12, s21, v1
	v_add_u32_e32 v13, 0x10200, v12
	v_add_u32_e32 v14, 0x10a00, v12
	v_lshl_add_u64 v[8:9], s[14:15], 0, v[8:9]
	v_lshl_add_u64 v[6:7], s[14:15], 0, v[6:7]
	s_addk_i32 s21, 0x1000
	v_cmp_eq_u32_e32 vcc, s21, v5
	v_add_u32_e32 v3, 0x400, v3
	v_add_u32_e32 v2, 0x400, v2
	s_or_b64 s[18:19], vcc, s[18:19]
	global_load_dword v8, v[8:9], off
	s_nop 0
	global_load_dword v6, v[6:7], off
	s_waitcnt vmcnt(2)
	ds_write_b32 v13, v10
	ds_write_b32 v14, v11
	v_add_u32_e32 v7, 0x11200, v12
	v_add_u32_e32 v9, 0x11a00, v12
	s_waitcnt vmcnt(1)
	ds_write_b32 v7, v8
	s_waitcnt vmcnt(0)
	ds_write_b32 v9, v6
	s_andn2_b64 exec, exec, s[18:19]
	s_cbranch_execnz .LBB0_576

; #define LAS __attribute__((address_space(3)))
; __device__ __forceinline__ void stage_ln_params(const float* g, const float* b, LAS float* gL, LAS float* bL, int tid) {
;     for (int i = tid; i < D_; i += 512) { gL[i] = g[i]; bL[i] = b[i]; }
; }
.LBB0_918:
	v_ashrrev_i32_e32 v9, 31, v0
	v_mov_b32_e32 v8, v0
	v_ashrrev_i32_e32 v7, 31, v1
	v_mov_b32_e32 v6, v1
	v_lshlrev_b64 v[8:9], 2, v[8:9]
	v_lshl_add_u64 v[10:11], s[6:7], 0, v[8:9]
	v_lshlrev_b64 v[6:7], 2, v[6:7]
	v_lshl_add_u64 v[12:13], s[6:7], 0, v[6:7]
	global_load_dword v5, v[10:11], off
	s_nop 0
	global_load_dword v10, v[12:13], off
	v_lshl_add_u64 v[8:9], s[14:15], 0, v[8:9]
	v_lshl_add_u64 v[6:7], s[14:15], 0, v[6:7]
	global_load_dword v14, v[8:9], off
	s_nop 0
	global_load_dword v6, v[6:7], off
	v_add_u32_e32 v3, -1, v3
	v_cmp_eq_u32_e32 vcc, 0, v3
	v_add_u32_e32 v1, 0x400, v1
	v_add_u32_e32 v0, 0x400, v0
	s_or_b64 s[18:19], vcc, s[18:19]
	v_add_u32_e32 v7, 0x1000, v4
	s_waitcnt vmcnt(2)
	ds_write2st64_b32 v4, v5, v10 offset1:8
	s_waitcnt vmcnt(0)
	ds_write2st64_b32 v4, v14, v6 offset0:16 offset1:24
	v_mov_b32_e32 v4, v7
	s_andn2_b64 exec, exec, s[18:19]
	s_cbranch_execnz .LBB0_918
